# v019 plus loop-edge edit: up-GEMM K-loop counter/pointer SALU moved from the SP1 load-segment head into the slack of the last load segment
# speedup vs baseline: 1.0057x; 1.0053x over previous
; #define PG8_STAGE(bufoff, gbase, voff) do { _Pragma("unroll") for (int _i = 0; _i < 2; ++_i) \
;         __builtin_amdgcn_global_load_lds((const unsigned*)((const char*)(gbase) + (voff)[_i]), (PG8_LAS unsigned*)(lds + (bufoff) + ldsw + _i * 8192), 16, 0, 0); } while (0)
; #define PG8_LDA(dst, b, h) do { _Pragma("unroll") for (int m = 0; m < 4; ++m) _Pragma("unroll") for (int k = 0; k < 2; ++k) dst[m][k] = *(const PG8_LAS bf16x8*)(lds + PG8_SA(b, h) + aoff + m * 2048 + k * 1024); } while (0)
; #define PG8_LDB(dst, b, h) do { _Pragma("unroll") for (int n = 0; n < 2; ++n) _Pragma("unroll") for (int k = 0; k < 2; ++k) dst[n][k] = *(const PG8_LAS bf16x8*)(lds + PG8_SB(b, h) + boff + n * 2048 + k * 1024); } while (0)
; #define PG8_MMA(ai, bj, At, Bt) do { __builtin_amdgcn_s_setprio(1); _Pragma("unroll") for (int m = 0; m < 4; ++m) _Pragma("unroll") for (int n = 0; n < 2; ++n) _Pragma("unroll") for (int k = 0; k < 2; ++k) \
;         acc[ai][bj][m][n] = __builtin_amdgcn_mfma_f32_16x16x32_bf16(Bt[n][k], At[m][k], acc[ai][bj][m][n], 0, 0, 0); __builtin_amdgcn_s_setprio(0); } while (0)
; #define PG8_WAIT_V(n) asm volatile("s_waitcnt vmcnt(" #n ")" ::: "memory")
; #define PG8_WAIT_L(n) asm volatile("s_waitcnt lgkmcnt(" #n ")" ::: "memory")
; #define PG8_BAR __builtin_amdgcn_s_barrier()
; #define PG8_SCHED __builtin_amdgcn_sched_barrier(0)
; template <class Epi, class Sched, bool ALIGN_EPI = false, bool SP2 = false>
; __device__ __forceinline__ void gemm_phase(PG8_LAS unsigned char* lds, const Gemm g, const Sched& S, const Epi& E) {
;     ...
;             PG8_LDB(B0, 0, 0); PG8_LDB(B1, 0, 1); PG8_SCHED; PG8_LDA(At, 0, 0); PG8_STAGE(PG8_SA(1, 1), a1 + hstep, voffA);
;             PG8_WAIT_V(8); PG8_WAIT_L(0); PG8_BAR; PG8_MMA(0, 0, At, B0); PG8_MMA(0, 1, At, B1); PG8_BAR; PG8_SCHED;
;             PG8_LDA(At, 0, 1); PG8_STAGE(PG8_SB(0, 0), b2, voffB); PG8_STAGE(PG8_SB(0, 1), b2 + hstep, voffB); PG8_STAGE(PG8_SA(0, 0), a2, voffA);
;             PG8_WAIT_V(8); PG8_WAIT_L(0); PG8_BAR; PG8_MMA(1, 0, At, B0); PG8_MMA(1, 1, At, B1); PG8_BAR; PG8_SCHED;
.Lup_kbody:
	v_add_u32_e32 v152, s81, v160
	v_add_u32_e32 v156, s84, v160
	ds_read_b128 v[140:143], v152
	ds_read_b128 v[144:147], v152 offset:1024
	ds_read_b128 v[148:151], v152 offset:2048
	ds_read_b128 v[152:155], v152 offset:3072
	ds_read_b128 v[164:167], v156
	ds_read_b128 v[180:183], v156 offset:1024
	ds_read_b128 v[184:187], v156 offset:2048
	ds_read_b128 v[190:193], v156 offset:3072
	v_lshl_add_u64 v[156:157], s[0:1], 0, v[136:137]
	s_add_i32 m0, s39, 0xc000
	ds_read_b128 v[194:197], v162
	ds_read_b128 v[198:201], v162 offset:1024
	ds_read_b128 v[202:205], v162 offset:2048
	ds_read_b128 v[206:209], v162 offset:3072
	ds_read_b128 v[210:213], v162 offset:4096
	ds_read_b128 v[214:217], v162 offset:5120
	ds_read_b128 v[218:221], v162 offset:6144
	ds_read_b128 v[232:235], v162 offset:7168
	global_load_lds_dwordx4 v[156:157], off
	v_lshl_add_u64 v[156:157], s[0:1], 0, v[138:139]
	s_add_i32 m0, s39, 0xe000
	s_nop 0
	global_load_lds_dwordx4 v[156:157], off
	s_waitcnt vmcnt(8)
	s_waitcnt lgkmcnt(0)
	s_barrier
	s_setprio 1
	s_waitcnt lgkmcnt(0)
	v_mfma_f32_16x16x32_bf16 v[126:129], v[140:143], v[194:197], v[126:129]
	v_mfma_f32_16x16x32_bf16 v[122:125], v[148:151], v[194:197], v[122:125]
	v_mfma_f32_16x16x32_bf16 v[110:113], v[140:143], v[202:205], v[110:113]
	v_mfma_f32_16x16x32_bf16 v[106:109], v[148:151], v[202:205], v[106:109]
	v_mfma_f32_16x16x32_bf16 v[94:97], v[140:143], v[210:213], v[94:97]
	v_mfma_f32_16x16x32_bf16 v[90:93], v[148:151], v[210:213], v[90:93]
	v_mfma_f32_16x16x32_bf16 v[78:81], v[140:143], v[218:221], v[78:81]
	v_mfma_f32_16x16x32_bf16 v[74:77], v[148:151], v[218:221], v[74:77]
	v_mfma_f32_16x16x32_bf16 v[126:129], v[144:147], v[198:201], v[126:129]
	v_mfma_f32_16x16x32_bf16 v[122:125], v[152:155], v[198:201], v[122:125]
	v_mfma_f32_16x16x32_bf16 v[110:113], v[144:147], v[206:209], v[110:113]
	v_mfma_f32_16x16x32_bf16 v[106:109], v[152:155], v[206:209], v[106:109]
	v_mfma_f32_16x16x32_bf16 v[94:97], v[144:147], v[214:217], v[94:97]
	v_mfma_f32_16x16x32_bf16 v[90:93], v[152:155], v[214:217], v[90:93]
	v_mfma_f32_16x16x32_bf16 v[78:81], v[144:147], v[232:235], v[78:81]
	v_mfma_f32_16x16x32_bf16 v[74:77], v[152:155], v[232:235], v[74:77]
	s_setprio 0
	s_setprio 1
	v_mfma_f32_16x16x32_bf16 v[118:121], v[164:167], v[194:197], v[118:121]
	v_mfma_f32_16x16x32_bf16 v[114:117], v[184:187], v[194:197], v[114:117]
	v_mfma_f32_16x16x32_bf16 v[102:105], v[164:167], v[202:205], v[102:105]
	v_mfma_f32_16x16x32_bf16 v[98:101], v[184:187], v[202:205], v[98:101]
	v_mfma_f32_16x16x32_bf16 v[86:89], v[164:167], v[210:213], v[86:89]
	v_mfma_f32_16x16x32_bf16 v[82:85], v[184:187], v[210:213], v[82:85]
	v_mfma_f32_16x16x32_bf16 v[70:73], v[164:167], v[218:221], v[70:73]
	v_mfma_f32_16x16x32_bf16 v[66:69], v[184:187], v[218:221], v[66:69]
	v_mfma_f32_16x16x32_bf16 v[118:121], v[180:183], v[198:201], v[118:121]
	v_mfma_f32_16x16x32_bf16 v[114:117], v[190:193], v[198:201], v[114:117]
	v_mfma_f32_16x16x32_bf16 v[102:105], v[180:183], v[206:209], v[102:105]
	v_mfma_f32_16x16x32_bf16 v[98:101], v[190:193], v[206:209], v[98:101]
	v_mfma_f32_16x16x32_bf16 v[86:89], v[180:183], v[214:217], v[86:89]
	v_mfma_f32_16x16x32_bf16 v[82:85], v[190:193], v[214:217], v[82:85]
	v_mfma_f32_16x16x32_bf16 v[70:73], v[180:183], v[232:235], v[70:73]
	v_mfma_f32_16x16x32_bf16 v[66:69], v[190:193], v[232:235], v[66:69]
	s_setprio 0
	s_barrier
	s_add_i32 s81, s81, s38
	v_lshl_add_u64 v[156:157], s[50:51], 0, v[0:1]
	s_mov_b32 m0, s81
	ds_read_b128 v[194:197], v162 offset:16384
	ds_read_b128 v[198:201], v162 offset:17408
	ds_read_b128 v[202:205], v162 offset:18432
	ds_read_b128 v[206:209], v162 offset:19456
	ds_read_b128 v[210:213], v162 offset:20480
	ds_read_b128 v[214:217], v162 offset:21504
	ds_read_b128 v[218:221], v162 offset:22528
	ds_read_b128 v[232:235], v162 offset:23552
	global_load_lds_dwordx4 v[156:157], off
	s_add_i32 m0, s81, 0x2000
	s_add_u32 s82, s50, 0x80000
	v_lshl_add_u64 v[168:169], s[50:51], 0, v[130:131]
	s_addc_u32 s83, s51, 0
	s_add_i32 s81, s84, s38
	global_load_lds_dwordx4 v[168:169], off
	v_lshl_add_u64 v[222:223], s[82:83], 0, v[0:1]
	s_mov_b32 m0, s81
	v_lshl_add_u64 v[236:237], s[52:53], 0, v[132:133]
	global_load_lds_dwordx4 v[222:223], off
	v_lshl_add_u64 v[222:223], s[82:83], 0, v[130:131]
	s_add_i32 m0, s81, 0x2000
	s_nop 0
	global_load_lds_dwordx4 v[222:223], off
	v_lshl_add_u64 v[222:223], s[52:53], 0, v[134:135]
	s_mov_b32 m0, s39
	s_nop 0
	global_load_lds_dwordx4 v[222:223], off
	s_mov_b32 m0, s58
	s_nop 0
	global_load_lds_dwordx4 v[236:237], off
	s_waitcnt vmcnt(8)
	s_waitcnt lgkmcnt(0)
	s_barrier
; #define PG8_STAGE(bufoff, gbase, voff) do { _Pragma("unroll") for (int _i = 0; _i < 2; ++_i) \
;         __builtin_amdgcn_global_load_lds((const unsigned*)((const char*)(gbase) + (voff)[_i]), (PG8_LAS unsigned*)(lds + (bufoff) + ldsw + _i * 8192), 16, 0, 0); } while (0)
; #define PG8_LDA(dst, b, h) do { _Pragma("unroll") for (int m = 0; m < 4; ++m) _Pragma("unroll") for (int k = 0; k < 2; ++k) dst[m][k] = *(const PG8_LAS bf16x8*)(lds + PG8_SA(b, h) + aoff + m * 2048 + k * 1024); } while (0)
; #define PG8_LDB(dst, b, h) do { _Pragma("unroll") for (int n = 0; n < 2; ++n) _Pragma("unroll") for (int k = 0; k < 2; ++k) dst[n][k] = *(const PG8_LAS bf16x8*)(lds + PG8_SB(b, h) + boff + n * 2048 + k * 1024); } while (0)
; #define PG8_MMA(ai, bj, At, Bt) do { __builtin_amdgcn_s_setprio(1); _Pragma("unroll") for (int m = 0; m < 4; ++m) _Pragma("unroll") for (int n = 0; n < 2; ++n) _Pragma("unroll") for (int k = 0; k < 2; ++k) \
;         acc[ai][bj][m][n] = __builtin_amdgcn_mfma_f32_16x16x32_bf16(Bt[n][k], At[m][k], acc[ai][bj][m][n], 0, 0, 0); __builtin_amdgcn_s_setprio(0); } while (0)
; #define PG8_WAIT_V(n) asm volatile("s_waitcnt vmcnt(" #n ")" ::: "memory")
; #define PG8_WAIT_L(n) asm volatile("s_waitcnt lgkmcnt(" #n ")" ::: "memory")
; #define PG8_BAR __builtin_amdgcn_s_barrier()
; #define PG8_SCHED __builtin_amdgcn_sched_barrier(0)
; template <class Epi, class Sched, bool ALIGN_EPI = false, bool SP2 = false>
; __device__ __forceinline__ void gemm_phase(PG8_LAS unsigned char* lds, const Gemm g, const Sched& S, const Epi& E) {
;     ...
;             PG8_WAIT_V(8); PG8_WAIT_L(0); PG8_BAR; PG8_MMA(1, 0, At, B0); PG8_MMA(1, 1, At, B1); PG8_BAR; PG8_SCHED;
;             PG8_LDB(B0, 1, 0); PG8_LDB(B1, 1, 1); PG8_SCHED; PG8_LDA(At, 1, 0); PG8_STAGE(PG8_SA(0, 1), a2 + hstep, voffA);
;             PG8_WAIT_V(8); PG8_WAIT_L(0); PG8_BAR; PG8_MMA(0, 0, At, B0); PG8_MMA(0, 1, At, B1); PG8_BAR; PG8_SCHED;
;             PG8_LDA(At, 1, 1); PG8_STAGE(PG8_SB(1, 0), b3, voffB); PG8_STAGE(PG8_SB(1, 1), b3 + hstep, voffB); PG8_STAGE(PG8_SA(1, 0), a3, voffA);
	s_setprio 1
	s_waitcnt lgkmcnt(0)
	v_mfma_f32_16x16x32_bf16 v[62:65], v[140:143], v[194:197], v[62:65]
	v_mfma_f32_16x16x32_bf16 v[58:61], v[148:151], v[194:197], v[58:61]
	v_mfma_f32_16x16x32_bf16 v[46:49], v[140:143], v[202:205], v[46:49]
	v_mfma_f32_16x16x32_bf16 v[42:45], v[148:151], v[202:205], v[42:45]
	v_mfma_f32_16x16x32_bf16 v[30:33], v[140:143], v[210:213], v[30:33]
	v_mfma_f32_16x16x32_bf16 v[26:29], v[148:151], v[210:213], v[26:29]
	v_mfma_f32_16x16x32_bf16 v[14:17], v[140:143], v[218:221], v[14:17]
	v_mfma_f32_16x16x32_bf16 v[10:13], v[148:151], v[218:221], v[10:13]
	v_mfma_f32_16x16x32_bf16 v[62:65], v[144:147], v[198:201], v[62:65]
	v_mfma_f32_16x16x32_bf16 v[58:61], v[152:155], v[198:201], v[58:61]
	v_mfma_f32_16x16x32_bf16 v[46:49], v[144:147], v[206:209], v[46:49]
	v_mfma_f32_16x16x32_bf16 v[42:45], v[152:155], v[206:209], v[42:45]
	v_mfma_f32_16x16x32_bf16 v[30:33], v[144:147], v[214:217], v[30:33]
	v_mfma_f32_16x16x32_bf16 v[26:29], v[152:155], v[214:217], v[26:29]
	v_mfma_f32_16x16x32_bf16 v[14:17], v[144:147], v[232:235], v[14:17]
	v_mfma_f32_16x16x32_bf16 v[10:13], v[152:155], v[232:235], v[10:13]
	s_setprio 0
	s_setprio 1
	v_mfma_f32_16x16x32_bf16 v[54:57], v[164:167], v[194:197], v[54:57]
	v_mfma_f32_16x16x32_bf16 v[50:53], v[184:187], v[194:197], v[50:53]
	v_mfma_f32_16x16x32_bf16 v[38:41], v[164:167], v[202:205], v[38:41]
	v_mfma_f32_16x16x32_bf16 v[34:37], v[184:187], v[202:205], v[34:37]
	v_mfma_f32_16x16x32_bf16 v[22:25], v[164:167], v[210:213], v[22:25]
	v_mfma_f32_16x16x32_bf16 v[18:21], v[184:187], v[210:213], v[18:21]
	v_mfma_f32_16x16x32_bf16 v[6:9], v[164:167], v[218:221], v[6:9]
	v_mfma_f32_16x16x32_bf16 v[2:5], v[184:187], v[218:221], v[2:5]
	v_mfma_f32_16x16x32_bf16 v[54:57], v[180:183], v[198:201], v[54:57]
	v_mfma_f32_16x16x32_bf16 v[50:53], v[190:193], v[198:201], v[50:53]
	v_mfma_f32_16x16x32_bf16 v[38:41], v[180:183], v[206:209], v[38:41]
	v_mfma_f32_16x16x32_bf16 v[34:37], v[190:193], v[206:209], v[34:37]
	v_mfma_f32_16x16x32_bf16 v[22:25], v[180:183], v[214:217], v[22:25]
	v_mfma_f32_16x16x32_bf16 v[18:21], v[190:193], v[214:217], v[18:21]
	v_mfma_f32_16x16x32_bf16 v[6:9], v[180:183], v[232:235], v[6:9]
	v_mfma_f32_16x16x32_bf16 v[2:5], v[190:193], v[232:235], v[2:5]
	s_setprio 0
	s_barrier
	s_add_i32 s81, 0, 0x18000
	s_add_i32 s82, 0, 0x1c000
	v_add_u32_e32 v152, s81, v160
	v_add_u32_e32 v158, s82, v160
	ds_read_b128 v[140:143], v152
	ds_read_b128 v[144:147], v152 offset:1024
	ds_read_b128 v[148:151], v152 offset:2048
	ds_read_b128 v[152:155], v152 offset:3072
	ds_read_b128 v[164:167], v158
	ds_read_b128 v[180:183], v158 offset:1024
	ds_read_b128 v[184:187], v158 offset:2048
	ds_read_b128 v[190:193], v158 offset:3072
	s_add_u32 s52, s52, 0x80000
	s_addc_u32 s53, s53, 0
	s_mov_b32 m0, s60
	v_lshl_add_u64 v[238:239], s[52:53], 0, v[134:135]
	ds_read_b128 v[194:197], v162 offset:32768
	ds_read_b128 v[198:201], v162 offset:33792
	ds_read_b128 v[202:205], v162 offset:34816
	ds_read_b128 v[206:209], v162 offset:35840
	ds_read_b128 v[210:213], v162 offset:36864
	ds_read_b128 v[214:217], v162 offset:37888
	ds_read_b128 v[218:221], v162 offset:38912
	ds_read_b128 v[232:235], v162 offset:39936
	global_load_lds_dwordx4 v[238:239], off
	v_lshl_add_u64 v[238:239], s[52:53], 0, v[132:133]
	s_mov_b32 m0, s61
	s_nop 0
	global_load_lds_dwordx4 v[238:239], off
	s_waitcnt vmcnt(8)
	s_waitcnt lgkmcnt(0)
	s_barrier
	s_setprio 1
	s_waitcnt lgkmcnt(0)
	v_mfma_f32_16x16x32_bf16 v[126:129], v[140:143], v[194:197], v[126:129]
	v_mfma_f32_16x16x32_bf16 v[122:125], v[148:151], v[194:197], v[122:125]
	v_mfma_f32_16x16x32_bf16 v[110:113], v[140:143], v[202:205], v[110:113]
	v_mfma_f32_16x16x32_bf16 v[106:109], v[148:151], v[202:205], v[106:109]
	v_mfma_f32_16x16x32_bf16 v[94:97], v[140:143], v[210:213], v[94:97]
	v_mfma_f32_16x16x32_bf16 v[90:93], v[148:151], v[210:213], v[90:93]
	v_mfma_f32_16x16x32_bf16 v[78:81], v[140:143], v[218:221], v[78:81]
	v_mfma_f32_16x16x32_bf16 v[74:77], v[148:151], v[218:221], v[74:77]
	v_mfma_f32_16x16x32_bf16 v[126:129], v[144:147], v[198:201], v[126:129]
	v_mfma_f32_16x16x32_bf16 v[122:125], v[152:155], v[198:201], v[122:125]
	v_mfma_f32_16x16x32_bf16 v[110:113], v[144:147], v[206:209], v[110:113]
	v_mfma_f32_16x16x32_bf16 v[106:109], v[152:155], v[206:209], v[106:109]
	v_mfma_f32_16x16x32_bf16 v[94:97], v[144:147], v[214:217], v[94:97]
	v_mfma_f32_16x16x32_bf16 v[90:93], v[152:155], v[214:217], v[90:93]
	v_mfma_f32_16x16x32_bf16 v[78:81], v[144:147], v[232:235], v[78:81]
	v_mfma_f32_16x16x32_bf16 v[74:77], v[152:155], v[232:235], v[74:77]
	s_setprio 0
	s_setprio 1
	v_mfma_f32_16x16x32_bf16 v[118:121], v[164:167], v[194:197], v[118:121]
	v_mfma_f32_16x16x32_bf16 v[114:117], v[184:187], v[194:197], v[114:117]
	v_mfma_f32_16x16x32_bf16 v[102:105], v[164:167], v[202:205], v[102:105]
	v_mfma_f32_16x16x32_bf16 v[98:101], v[184:187], v[202:205], v[98:101]
	v_mfma_f32_16x16x32_bf16 v[86:89], v[164:167], v[210:213], v[86:89]
	v_mfma_f32_16x16x32_bf16 v[82:85], v[184:187], v[210:213], v[82:85]
	v_mfma_f32_16x16x32_bf16 v[70:73], v[164:167], v[218:221], v[70:73]
	v_mfma_f32_16x16x32_bf16 v[66:69], v[184:187], v[218:221], v[66:69]
	v_mfma_f32_16x16x32_bf16 v[118:121], v[180:183], v[198:201], v[118:121]
	v_mfma_f32_16x16x32_bf16 v[114:117], v[190:193], v[198:201], v[114:117]
	v_mfma_f32_16x16x32_bf16 v[102:105], v[180:183], v[206:209], v[102:105]
	v_mfma_f32_16x16x32_bf16 v[98:101], v[190:193], v[206:209], v[98:101]
	v_mfma_f32_16x16x32_bf16 v[86:89], v[180:183], v[214:217], v[86:89]
	v_mfma_f32_16x16x32_bf16 v[82:85], v[190:193], v[214:217], v[82:85]
	v_mfma_f32_16x16x32_bf16 v[70:73], v[180:183], v[232:235], v[70:73]
	v_mfma_f32_16x16x32_bf16 v[66:69], v[190:193], v[232:235], v[66:69]
	s_setprio 0
	s_barrier
; #define PG8_STAGE(bufoff, gbase, voff) do { _Pragma("unroll") for (int _i = 0; _i < 2; ++_i) \
;         __builtin_amdgcn_global_load_lds((const unsigned*)((const char*)(gbase) + (voff)[_i]), (PG8_LAS unsigned*)(lds + (bufoff) + ldsw + _i * 8192), 16, 0, 0); } while (0)
; #define PG8_LDA(dst, b, h) do { _Pragma("unroll") for (int m = 0; m < 4; ++m) _Pragma("unroll") for (int k = 0; k < 2; ++k) dst[m][k] = *(const PG8_LAS bf16x8*)(lds + PG8_SA(b, h) + aoff + m * 2048 + k * 1024); } while (0)
; #define PG8_MMA(ai, bj, At, Bt) do { __builtin_amdgcn_s_setprio(1); _Pragma("unroll") for (int m = 0; m < 4; ++m) _Pragma("unroll") for (int n = 0; n < 2; ++n) _Pragma("unroll") for (int k = 0; k < 2; ++k) \
;         acc[ai][bj][m][n] = __builtin_amdgcn_mfma_f32_16x16x32_bf16(Bt[n][k], At[m][k], acc[ai][bj][m][n], 0, 0, 0); __builtin_amdgcn_s_setprio(0); } while (0)
; #define PG8_WAIT_V(n) asm volatile("s_waitcnt vmcnt(" #n ")" ::: "memory")
; #define PG8_WAIT_L(n) asm volatile("s_waitcnt lgkmcnt(" #n ")" ::: "memory")
; #define PG8_BAR __builtin_amdgcn_s_barrier()
; #define PG8_SCHED __builtin_amdgcn_sched_barrier(0)
; template <class Epi, class Sched, bool ALIGN_EPI = false, bool SP2 = false>
; __device__ __forceinline__ void gemm_phase(PG8_LAS unsigned char* lds, const Gemm g, const Sched& S, const Epi& E) {
;     ...
;         for (int t = 0; t < nt; t += 2) {
;             const bool last = (t == nt - 2);
;             const char* a1 = cA + (size_t)(t + 1) * kstep;
;             const char* a2 = last ? nA : cA + (size_t)(t + 2) * kstep; const char* b2 = last ? nB : cB + (size_t)(t + 2) * kstep;
;             const char* a3 = a2 + kstep; const char* b3 = b2 + kstep;
;             if (last && has_next) S.a_ready(nxt);
;     ...
;             PG8_LDA(At, 1, 1); PG8_STAGE(PG8_SB(1, 0), b3, voffB); PG8_STAGE(PG8_SB(1, 1), b3 + hstep, voffB); PG8_STAGE(PG8_SA(1, 0), a3, voffA);
;             PG8_WAIT_V(8); PG8_WAIT_L(0); PG8_BAR; PG8_MMA(1, 0, At, B0); PG8_MMA(1, 1, At, B1); PG8_BAR; PG8_SCHED;
	s_add_i32 s52, s81, s38
	v_lshl_add_u64 v[156:157], v[156:157], 0, s[12:13]
	s_mov_b32 m0, s52
	ds_read_b128 v[194:197], v162 offset:49152
	ds_read_b128 v[198:201], v162 offset:50176
	ds_read_b128 v[202:205], v162 offset:51200
	ds_read_b128 v[206:209], v162 offset:52224
	ds_read_b128 v[210:213], v162 offset:53248
	ds_read_b128 v[214:217], v162 offset:54272
	ds_read_b128 v[218:221], v162 offset:55296
	ds_read_b128 v[232:235], v162 offset:56320
	global_load_lds_dwordx4 v[156:157], off
	s_add_i32 m0, s52, 0x2000
	s_add_u32 s50, s50, 0x80080
	v_lshl_add_u64 v[156:157], v[168:169], 0, s[12:13]
	s_addc_u32 s51, s51, 0
	s_add_i32 s52, s82, s38
	global_load_lds_dwordx4 v[156:157], off
	v_lshl_add_u64 v[156:157], s[50:51], 0, v[0:1]
	s_mov_b32 m0, s52
	s_nop 0
	global_load_lds_dwordx4 v[156:157], off
	v_lshl_add_u64 v[156:157], s[50:51], 0, v[130:131]
	s_add_i32 m0, s52, 0x2000
	s_nop 0
	global_load_lds_dwordx4 v[156:157], off
	v_lshl_add_u64 v[156:157], v[222:223], 0, s[12:13]
	s_mov_b32 m0, s62
	s_nop 0
	global_load_lds_dwordx4 v[156:157], off
	v_lshl_add_u64 v[156:157], v[236:237], 0, s[12:13]
	s_mov_b32 m0, s63
	s_nop 0
	global_load_lds_dwordx4 v[156:157], off
	s_add_i32 s80, s80, 2
	s_add_u32 s0, s0, 0x100
	s_addc_u32 s1, s1, 0
	s_add_u32 s74, s74, 0x100
	s_addc_u32 s75, s75, 0
	s_add_u32 s50, s0, 0xfff80080
	s_addc_u32 s51, s1, -1
	s_add_i32 s81, 0, 0x10000
	s_cmp_eq_u32 s80, 28
	s_cselect_b32 s53, s24, s51
	s_cselect_b32 s52, s25, s50
	s_cselect_b32 s51, s43, s75
	s_cselect_b32 s50, s45, s74
	s_add_i32 s84, 0, 0x14000
	s_waitcnt vmcnt(8)
	s_waitcnt lgkmcnt(0)
	s_barrier
	s_setprio 1
	s_waitcnt lgkmcnt(0)
	v_mfma_f32_16x16x32_bf16 v[62:65], v[140:143], v[194:197], v[62:65]
	v_mfma_f32_16x16x32_bf16 v[58:61], v[148:151], v[194:197], v[58:61]
	v_mfma_f32_16x16x32_bf16 v[46:49], v[140:143], v[202:205], v[46:49]
	v_mfma_f32_16x16x32_bf16 v[42:45], v[148:151], v[202:205], v[42:45]
	v_mfma_f32_16x16x32_bf16 v[30:33], v[140:143], v[210:213], v[30:33]
	v_mfma_f32_16x16x32_bf16 v[26:29], v[148:151], v[210:213], v[26:29]
	v_mfma_f32_16x16x32_bf16 v[14:17], v[140:143], v[218:221], v[14:17]
	v_mfma_f32_16x16x32_bf16 v[10:13], v[148:151], v[218:221], v[10:13]
	v_mfma_f32_16x16x32_bf16 v[62:65], v[144:147], v[198:201], v[62:65]
	v_mfma_f32_16x16x32_bf16 v[58:61], v[152:155], v[198:201], v[58:61]
	v_mfma_f32_16x16x32_bf16 v[46:49], v[144:147], v[206:209], v[46:49]
	v_mfma_f32_16x16x32_bf16 v[42:45], v[152:155], v[206:209], v[42:45]
	v_mfma_f32_16x16x32_bf16 v[30:33], v[144:147], v[214:217], v[30:33]
	v_mfma_f32_16x16x32_bf16 v[26:29], v[152:155], v[214:217], v[26:29]
	v_mfma_f32_16x16x32_bf16 v[14:17], v[144:147], v[232:235], v[14:17]
	v_mfma_f32_16x16x32_bf16 v[10:13], v[152:155], v[232:235], v[10:13]
	s_setprio 0
	s_setprio 1
	v_mfma_f32_16x16x32_bf16 v[54:57], v[164:167], v[194:197], v[54:57]
	v_mfma_f32_16x16x32_bf16 v[50:53], v[184:187], v[194:197], v[50:53]
	v_mfma_f32_16x16x32_bf16 v[38:41], v[164:167], v[202:205], v[38:41]
	v_mfma_f32_16x16x32_bf16 v[34:37], v[184:187], v[202:205], v[34:37]
	v_mfma_f32_16x16x32_bf16 v[22:25], v[164:167], v[210:213], v[22:25]
	v_mfma_f32_16x16x32_bf16 v[18:21], v[184:187], v[210:213], v[18:21]
	v_mfma_f32_16x16x32_bf16 v[6:9], v[164:167], v[218:221], v[6:9]
	v_mfma_f32_16x16x32_bf16 v[2:5], v[184:187], v[218:221], v[2:5]
	v_mfma_f32_16x16x32_bf16 v[54:57], v[180:183], v[198:201], v[54:57]
	v_mfma_f32_16x16x32_bf16 v[50:53], v[190:193], v[198:201], v[50:53]
	v_mfma_f32_16x16x32_bf16 v[38:41], v[180:183], v[206:209], v[38:41]
	v_mfma_f32_16x16x32_bf16 v[34:37], v[190:193], v[206:209], v[34:37]
	v_mfma_f32_16x16x32_bf16 v[22:25], v[180:183], v[214:217], v[22:25]
	v_mfma_f32_16x16x32_bf16 v[18:21], v[190:193], v[214:217], v[18:21]
	v_mfma_f32_16x16x32_bf16 v[6:9], v[180:183], v[232:235], v[6:9]
	v_mfma_f32_16x16x32_bf16 v[2:5], v[190:193], v[232:235], v[2:5]
	s_setprio 0
	s_barrier
	s_cmp_gt_u32 s80, 29
	s_cbranch_scc0 .Lup_kbody
	s_and_b64 vcc, exec, s[30:31]
	s_cbranch_vccz .LBB0_1500
	s_barrier
